# attention: bias MFMAs take C=0 (zero fill deleted), A2 Q-fragment waits hoisted out of the step loop, B K/V two steps ahead
# speedup vs baseline: 1.0125x; 1.0125x over previous
.LBB0_539:
	s_lshl_b32 s8, s14, 7
	s_lshl_b32 s17, s14, 1
	s_or_b32 s16, s8, s51
	s_add_i32 s8, s17, -8
	s_cmp_gt_u32 s14, 4
	s_cselect_b32 s18, s8, 0
	v_or_b32_e32 v0, s16, v163
	v_lshlrev_b32_e32 v0, 7, v0
	s_lshl_b32 s8, s18, 6
	v_lshl_add_u64 v[2:3], v[164:165], 0, v[0:1]
	v_or_b32_e32 v0, s8, v202
	v_lshlrev_b64 v[4:5], 7, v[0:1]
	v_lshl_or_b32 v4, v162, 1, v4
	v_lshl_add_u64 v[6:7], s[4:5], 0, v[4:5]
	global_load_dwordx4 v[66:69], v[6:7], off offset:16
	global_load_dwordx4 v[70:73], v[6:7], off
	v_lshl_add_u64 v[4:5], s[6:7], 0, v[4:5]
	global_load_dwordx4 v[90:93], v[4:5], off
	global_load_dwordx4 v[94:97], v[4:5], off offset:16
	global_load_dwordx4 v[74:77], v[2:3], off
	global_load_dwordx4 v[78:81], v[2:3], off offset:32
	global_load_dwordx4 v[82:85], v[2:3], off offset:64
	global_load_dwordx4 v[86:89], v[2:3], off offset:96
	s_or_b32 s9, s17, 1
	s_cmp_gt_i32 s18, s9
	s_waitcnt vmcnt(6)
	ds_write_b128 v203, v[70:73]
	ds_write_b128 v203, v[66:69] offset:16
	s_waitcnt vmcnt(5)
	ds_write_b128 v203, v[90:93] offset:18432
	s_waitcnt vmcnt(4)
	ds_write_b128 v203, v[94:97] offset:18448
	s_waitcnt vmcnt(0)
	s_waitcnt lgkmcnt(0)
	s_barrier
	s_cbranch_scc1 .LBB0_552
	s_lshr_b32 s19, s16, 6
	s_add_i32 s9, s19, -8
	s_cmpk_gt_u32 s16, 0x23f
	v_mov_b32_e32 v210, 0
	s_cselect_b32 s20, s9, 0
	s_sub_i32 s21, 0, s8
	v_subrev_u32_e32 v211, s8, v208
	v_add_u32_e32 v200, s8, v209
	s_mov_b32 s22, s15
	v_mov_b32_e32 v2, 0
	v_mov_b32_e32 v3, v210
	v_mov_b32_e32 v4, v210
	v_mov_b32_e32 v5, v210
	v_mov_b32_e32 v6, v210
	v_mov_b32_e32 v7, v210
	v_mov_b32_e32 v8, v210
	v_mov_b32_e32 v9, v210
	v_mov_b32_e32 v10, v210
	v_mov_b32_e32 v11, v210
	v_mov_b32_e32 v12, v210
	v_mov_b32_e32 v13, v210
	v_mov_b32_e32 v14, v210
	v_mov_b32_e32 v15, v210
	v_mov_b32_e32 v16, v210
	v_mov_b32_e32 v17, v210
	v_mov_b32_e32 v18, 0
	v_mov_b32_e32 v19, v210
	v_mov_b32_e32 v20, v210
	v_mov_b32_e32 v21, v210
	v_mov_b32_e32 v22, v210
	v_mov_b32_e32 v23, v210
	v_mov_b32_e32 v24, v210
	v_mov_b32_e32 v25, v210
	v_mov_b32_e32 v26, v210
	v_mov_b32_e32 v27, v210
	v_mov_b32_e32 v28, v210
	v_mov_b32_e32 v29, v210
	v_mov_b32_e32 v30, v210
	v_mov_b32_e32 v31, v210
	v_mov_b32_e32 v32, v210
	v_mov_b32_e32 v33, v210
	s_branch .LBB0_542

.LBB0_549:
	s_waitcnt lgkmcnt(1)
	s_nop 0
	v_mfma_f32_32x32x16_bf16 v[50:65], v[154:157], v[74:77], v[50:65]
	s_waitcnt lgkmcnt(0)
	v_mfma_f32_32x32x16_bf16 v[34:49], v[158:161], v[74:77], v[34:49]
	v_mfma_f32_32x32x16_bf16 v[50:65], v[142:145], v[78:81], v[50:65]
	v_mfma_f32_32x32x16_bf16 v[34:49], v[146:149], v[78:81], v[34:49]
	v_mfma_f32_32x32x16_bf16 v[50:65], v[138:141], v[82:85], v[50:65]
	v_mfma_f32_32x32x16_bf16 v[34:49], v[150:153], v[82:85], v[34:49]
	v_mfma_f32_32x32x16_bf16 v[50:65], v[134:137], v[86:89], v[50:65]
	v_mfma_f32_32x32x16_bf16 v[34:49], v[130:133], v[86:89], v[34:49]
	s_nop 10
	v_exp_f32_e32 v134, v50
	v_exp_f32_e32 v133, v58
	v_exp_f32_e32 v58, v59
	v_exp_f32_e32 v130, v34
	v_exp_f32_e32 v34, v51
	v_exp_f32_e32 v0, v35
	v_exp_f32_e32 v131, v36
	v_add_f32_e32 v35, v134, v130
	v_exp_f32_e32 v36, v53
	v_pk_add_f32 v[50:51], v[34:35], v[0:1]
	v_exp_f32_e32 v35, v52
	v_pk_add_f32 v[50:51], v[50:51], v[50:51] op_sel_hi:[0,1]
	v_exp_f32_e32 v50, v37
	v_cvt_pk_bf16_f32 v34, v134, v34
	v_add_f32_e32 v37, v35, v131
	v_cvt_pk_bf16_f32 v35, v35, v36
	v_pk_add_f32 v[52:53], v[36:37], v[50:51]
	v_exp_f32_e32 v37, v54
	v_pk_add_f32 v[52:53], v[52:53], v[52:53] op_sel_hi:[0,1]
	v_exp_f32_e32 v51, v38
	v_exp_f32_e32 v38, v55
	v_exp_f32_e32 v52, v39
	v_exp_f32_e32 v132, v40
	v_add_f32_e32 v39, v37, v51
	v_cvt_pk_bf16_f32 v36, v37, v38
	v_pk_add_f32 v[54:55], v[38:39], v[52:53]
	v_exp_f32_e32 v53, v56
	v_exp_f32_e32 v56, v57
	v_pk_add_f32 v[54:55], v[54:55], v[54:55] op_sel_hi:[0,1]
	v_exp_f32_e32 v54, v41
	v_add_f32_e32 v57, v53, v132
	v_cvt_pk_bf16_f32 v37, v53, v56
	v_exp_f32_e32 v53, v42
	v_cvt_pk_bf16_f32 v38, v133, v58
	v_mfma_f32_32x32x16_bf16 v[2:17], v[34:37], v[126:129], v[2:17]
	v_exp_f32_e32 v126, v60
	v_exp_f32_e32 v60, v61
	v_exp_f32_e32 v127, v62
	v_exp_f32_e32 v62, v63
	v_exp_f32_e32 v128, v64
	v_exp_f32_e32 v64, v65
	v_add_f32_e32 v59, v133, v53
	v_mfma_f32_32x32x16_bf16 v[18:33], v[34:37], v[122:125], v[18:33]
	v_add_f32_e64 v34, v56, v54
	v_add_f32_e64 v35, v57, v55
	v_cvt_pk_bf16_f32 v39, v126, v60
	v_add_f32_e64 v56, v34, v34
	v_add_f32_e64 v57, v34, v35
	v_exp_f32_e32 v56, v43
	v_cvt_pk_bf16_f32 v40, v127, v62
	v_cvt_pk_bf16_f32 v41, v128, v64
	v_exp_f32_e32 v55, v44
	v_pk_add_f32 v[34:35], v[58:59], v[56:57]
	v_mfma_f32_32x32x16_bf16 v[2:17], v[38:41], v[118:121], v[2:17]
	v_add_f32_e64 v42, v34, v34
	v_add_f32_e64 v43, v34, v35
	v_exp_f32_e32 v42, v45
	v_add_f32_e32 v61, v126, v55
	v_cvt_pk_bf16_f32 v34, v130, v0
	v_exp_f32_e32 v0, v46
	v_cvt_pk_bf16_f32 v35, v131, v50
	v_cvt_pk_bf16_f32 v36, v51, v52
	v_mfma_f32_32x32x16_bf16 v[18:33], v[38:41], v[114:117], v[18:33]
	v_add_f32_e64 v38, v60, v42
	v_add_f32_e64 v39, v61, v43
	v_cvt_pk_bf16_f32 v37, v132, v54
	v_add_f32_e64 v40, v38, v38
	v_add_f32_e64 v41, v38, v39
	v_exp_f32_e32 v40, v47
	v_add_f32_e32 v63, v127, v0
	v_exp_f32_e32 v43, v48
	v_pk_add_f32 v[38:39], v[62:63], v[40:41]
	s_nop 0
	v_pk_add_f32 v[44:45], v[38:39], v[38:39] op_sel_hi:[0,1]
	v_exp_f32_e32 v44, v49
	v_mfma_f32_32x32x16_bf16 v[2:17], v[34:37], v[110:113], v[2:17]
	v_cvt_pk_bf16_f32 v38, v53, v56
	v_cvt_pk_bf16_f32 v39, v55, v42
	v_cvt_pk_bf16_f32 v40, v0, v40
	v_cvt_pk_bf16_f32 v41, v43, v44
	v_add_f32_e32 v65, v128, v43
	v_mfma_f32_32x32x16_bf16 v[18:33], v[34:37], v[106:109], v[18:33]
	v_add_f32_e64 v34, v64, v44
	v_add_f32_e64 v35, v65, v45
	v_add_f32_e32 v0, v34, v35
	v_add_f32_e32 v210, v210, v0
	v_mfma_f32_32x32x16_bf16 v[2:17], v[38:41], v[102:105], v[2:17]
	v_mfma_f32_32x32x16_bf16 v[18:33], v[38:41], v[98:101], v[18:33]

.LBB0_591:
	s_andn2_b64 vcc, exec, s[16:17]
	s_cbranch_vccnz .LBB0_593
	ds_read2_b64 v[180:183], v252 offset1:32
	s_waitcnt lgkmcnt(1)
	v_mov_b32_e32 v188, 0x3f803f80
	v_mov_b32_e32 v184, 0x3f803f80
	v_mov_b32_e32 v189, 0
	s_and_b64 vcc, exec, s[4:5]
	s_cbranch_vccz .LBB0_594
	s_branch .LBB0_595

.LBB0_594:
	s_waitcnt lgkmcnt(0)
	v_mov_b32_e32 v186, v180
	v_mov_b32_e32 v187, v181
	v_mov_b32_e32 v185, v189
	s_nop 0
	v_mfma_f32_32x32x16_bf16 v[64:79], v[186:189], v[80:83], 0
	v_mfma_f32_32x32x16_bf16 v[48:63], v[182:185], v[80:83], 0

.LBB0_605:
	s_andn2_b64 vcc, exec, s[16:17]
	s_cbranch_vccnz .LBB0_607
	ds_read2_b64 v[180:183], v252 offset0:64 offset1:96
	s_waitcnt lgkmcnt(1)
	v_mov_b32_e32 v188, 0x3f803f80
	v_mov_b32_e32 v184, 0x3f803f80
	v_mov_b32_e32 v189, 0
	s_and_b64 vcc, exec, s[4:5]
	s_cbranch_vccz .LBB0_608
	s_branch .LBB0_609
